# gated-DeltaNet: output work balanced over the four waves (own row quarter each), O MFMA issued after the state update
# speedup vs baseline: 1.0021x; 1.0021x over previous
; __device__ __forceinline__ int otid() { int t = threadIdx.x; asm volatile("" : "+v"(t)); return t; }
; __device__ __forceinline__ void gdn_item(const Params& p, int item, float* sm) {
;   const int b = item >> 5, h = (item >> 3) & 3, c0 = (item & 7) * 16;
;   const bf16_t* gp = (const bf16_t*)p.out;
;   const float* gg = (const float*)(p.ws + OFF_GG);
;   bf16_t* O = (bf16_t*)(p.ws + OFF_O);
;   constexpr int TC = 16;
;   constexpr int BUF = 2 * TC * 128 + TC * 16 + 2 * TC + TC * 16 + TC;
;   const int tid = otid(), lane = tid & 63, wave = tid >> 6;
;   const int sub = lane & 15, cw = wave * 4 + (lane >> 4);
;   const int ltt = tid >> 4, lseg = tid & 15;
;   float S[8];
; #pragma unroll
;   for (int i = 0; i < 8; i++) S[i] = 0.f;
;   const size_t rowb = (size_t)b * LP;
;   uint4 pq, pk; bf16_t pv; float pg = 0.f, pb = 0.f;
;     ...
;   __syncthreads();
;   GDN_LOAD(PADR)
;   GDN_STORE(0)
;   __syncthreads();
.Lgd_item:
	s_setprio 3
	v_readlane_b32 s14, v244, 27
	v_readlane_b32 s8, v247, 3
	v_readlane_b32 s9, v247, 4
	v_readlane_b32 s4, v247, 1
	v_readlane_b32 s5, v247, 2
	v_and_b32_e32 v136, 15, v2
	v_lshrrev_b32_e32 v137, 4, v2
	v_bfe_u32 v138, v2, 4, 2
	v_lshrrev_b32_e32 v139, 6, v2
	s_lshr_b32 s10, s14, 5
	s_bfe_u32 s11, s14, 0x20003
	s_and_b32 s12, s14, 7
	s_lshl_b32 s12, s12, 5
	s_mul_i32 s13, s10, 0x2080
	s_add_i32 s13, s13, 0x70
	s_add_u32 s6, s8, 0x19c8c000
	s_addc_u32 s7, s9, 0
	s_add_u32 s8, s8, 0x19d90000
	s_addc_u32 s9, s9, 0
	s_lshl_b32 s14, s10, 2
	s_add_i32 s14, s14, s11
	s_mul_i32 s14, s14, 0x80400
	s_add_u32 s10, s4, 0x71a0000
	s_addc_u32 s15, s5, 0
	s_add_u32 s10, s10, s14
	s_addc_u32 s11, s15, 0
	v_readfirstlane_b32 s100, v139
	v_lshlrev_b32_e32 v151, 9, v136
	v_lshl_add_u32 v151, v139, 7, v151
	v_lshl_add_u32 v151, v138, 4, v151
	v_lshlrev_b32_e32 v152, 11, v138
	v_lshl_add_u32 v152, v139, 7, v152
	v_lshl_add_u32 v152, v136, 2, v152
	v_lshlrev_b32_e32 v153, 6, v136
	v_lshl_add_u32 v153, v138, 4, v153
	v_lshlrev_b32_e32 v154, 4, v138
	v_and_b32_e32 v140, 63, v2
	v_lshlrev_b32_e32 v156, 4, v140
	v_add_u32_e32 v156, 0x8a00, v156
	s_mul_i32 s101, s100, 0xc00
	v_add_u32_e32 v155, s101, v156
	v_lshlrev_b32_e32 v157, 5, v2
	v_lshl_add_u32 v158, v136, 4, v137
	v_lshlrev_b32_e32 v158, 2, v158
	v_add_u32_e32 v158, 16384, v158
	v_lshlrev_b32_e32 v159, 2, v136
	v_lshlrev_b32_e32 v141, 2, v138
	v_add_u32_e32 v142, 0, v141
	v_cmp_le_u32_e32 vcc, v142, v136
	s_nop 1
	v_cndmask_b32_e64 v166, 0, 1.0, vcc
	v_add_u32_e32 v142, 1, v141
	v_cmp_le_u32_e32 vcc, v142, v136
	s_nop 1
	v_cndmask_b32_e64 v167, 0, 1.0, vcc
	v_add_u32_e32 v142, 2, v141
	v_cmp_le_u32_e32 vcc, v142, v136
	s_nop 1
	v_cndmask_b32_e64 v168, 0, 1.0, vcc
	v_add_u32_e32 v142, 3, v141
	v_cmp_le_u32_e32 vcc, v142, v136
	s_nop 1
	v_cndmask_b32_e64 v169, 0, 1.0, vcc
	v_readlane_b32 s101, v244, 27
	s_bfe_u32 s101, s101, 0x20003
	v_add_u32_e32 v142, s13, v137
	s_lshl_b32 s14, s101, 8
	v_lshl_add_u32 v143, v136, 4, s14
	s_movk_i32 s15, 0xc00
	v_mad_u32_u24 v118, v142, s15, v143
	s_add_i32 s14, s14, s12
	v_lshl_add_u32 v143, v136, 1, s14
	v_mad_u32_u24 v119, v142, s15, v143
	v_add_u32_e32 v119, 0x800, v119
	v_add_u32_e32 v142, s13, v136
	s_lshl_b32 s15, s101, 2
	v_lshl_add_u32 v140, v142, 5, s15
	v_add_u32_e32 v142, s13, v141
	v_lshl_add_u32 v57, v142, 11, v143
	v_add_u32_e32 v57, 0x400, v57
	v_add_u32_e32 v58, 0x1000, v57
	v_lshlrev_b32_e32 v59, 6, v136
	v_lshl_add_u32 v59, v138, 4, v59
	v_cmp_eq_u32_e32 vcc, 0, v139
	s_nop 1
	v_cndmask_b32_e64 v170, 0, 1.0, vcc
	v_cmp_eq_u32_e32 vcc, 1, v139
	s_nop 1
	v_cndmask_b32_e64 v171, 0, 1.0, vcc
	v_cmp_eq_u32_e32 vcc, 2, v139
	s_nop 1
	v_cndmask_b32_e64 v172, 0, 1.0, vcc
	v_cmp_eq_u32_e32 vcc, 3, v139
	s_nop 1
	v_cndmask_b32_e64 v173, 0, 1.0, vcc
	v_lshl_add_u32 v179, v139, 2, v59
	v_mov_b32_e32 v174, 0
	v_mov_b32_e32 v175, 0
	v_mov_b32_e32 v176, 0
	v_mov_b32_e32 v177, 0
	v_lshl_add_u32 v184, v139, 2, v156
	v_add_u32_e32 v184, 0x400, v184
	v_lshl_add_u32 v185, v139, 11, v57
	s_sub_u32 s8, s8, 0x8000
	s_subb_u32 s9, s9, 0
	v_readlane_b32 s14, v244, 27
	s_lshr_b32 s14, s14, 3
	s_mul_i32 s12, s14, 0x80400
	v_readlane_b32 s14, v247, 3
	v_readlane_b32 s15, v247, 4
	s_add_u32 s14, s14, 0xac40000
	s_addc_u32 s15, s15, 0
	s_add_u32 s14, s14, s12
	s_addc_u32 s15, s15, 0
	v_mov_b32_e32 v12, 0
	v_mov_b32_e32 v13, 0
	v_mov_b32_e32 v14, 0
	v_mov_b32_e32 v15, 0
	v_mov_b32_e32 v16, 0
	v_mov_b32_e32 v17, 0
	v_mov_b32_e32 v18, 0
	v_mov_b32_e32 v19, 0
	s_barrier
	global_load_dwordx4 v[108:111], v118, s[4:5]
	global_load_dwordx4 v[112:115], v118, s[4:5] offset:1024
	global_load_ushort v116, v119, s[4:5]
	global_load_dword v117, v140, s[6:7]
	s_add_u32 s4, s4, 0xc000
	s_addc_u32 s5, s5, 0
	s_add_u32 s6, s6, 0x200
	s_addc_u32 s7, s7, 0
	global_load_dwordx4 v[88:91], v59, s[10:11]
	s_add_u32 s10, s10, 0x400
	s_addc_u32 s11, s11, 0
	global_load_dword v92, v179, s[14:15]
	s_add_u32 s14, s14, 0x400
	s_addc_u32 s15, s15, 0
	v_mov_b32_e32 v148, v157
	v_mov_b32_e32 v149, v158
	v_mov_b32_e32 v150, v159
	s_waitcnt vmcnt(0)
	v_lshlrev_b32_e32 v120, 16, v108
	v_and_b32_e32 v121, 0xffff0000, v108
	v_lshlrev_b32_e32 v122, 16, v109
	v_and_b32_e32 v123, 0xffff0000, v109
	v_lshlrev_b32_e32 v124, 16, v110
	v_and_b32_e32 v125, 0xffff0000, v110
	v_lshlrev_b32_e32 v126, 16, v111
	v_and_b32_e32 v127, 0xffff0000, v111
	v_lshlrev_b32_e32 v128, 16, v112
	v_and_b32_e32 v129, 0xffff0000, v112
	v_lshlrev_b32_e32 v130, 16, v113
	v_and_b32_e32 v131, 0xffff0000, v113
	v_lshlrev_b32_e32 v132, 16, v114
	v_and_b32_e32 v133, 0xffff0000, v114
	v_lshlrev_b32_e32 v134, 16, v115
	v_and_b32_e32 v135, 0xffff0000, v115
	v_mov_b32_e32 v136, v117
	v_lshlrev_b32_e32 v137, 16, v116
	s_nop 0
	v_add_f32_dpp v136, v136, v136 row_shr:1 row_mask:0xf bank_mask:0xf bound_ctrl:1
	s_nop 1
	v_add_f32_dpp v136, v136, v136 row_shr:2 row_mask:0xf bank_mask:0xf bound_ctrl:1
	s_nop 1
	v_add_f32_dpp v136, v136, v136 row_shr:4 row_mask:0xf bank_mask:0xf bound_ctrl:1
	s_nop 1
	v_add_f32_dpp v136, v136, v136 row_shr:8 row_mask:0xf bank_mask:0xf bound_ctrl:1
	s_nop 0
	v_max_f32_e32 v136, 0xc2a00000, v136
	v_mul_f32_e32 v136, 0x3fb8aa3b, v136
	v_exp_f32_e32 v138, v136
	v_exp_f32_e64 v139, -v136
	s_nop 0
	v_mul_f32_e32 v136, 0x3db504f3, v138
	ds_write_b128 v148, v[120:123]
	ds_write_b128 v148, v[124:127] offset:16
	ds_write_b128 v148, v[128:131] offset:8192
	ds_write_b128 v148, v[132:135] offset:8208
	ds_write_b32 v149, v137
	ds_write_b32 v150, v139 offset:17408
	ds_write_b32 v150, v138 offset:17536
	ds_write_b32 v150, v136 offset:17472
	global_load_dwordx4 v[108:111], v118, s[4:5]
	global_load_dwordx4 v[112:115], v118, s[4:5] offset:1024
	global_load_ushort v116, v119, s[4:5]
	global_load_dword v117, v140, s[6:7]
	s_add_u32 s4, s4, 0xc000
	s_addc_u32 s5, s5, 0
	s_add_u32 s6, s6, 0x200
	s_addc_u32 s7, s7, 0
	s_mov_b32 s0, 0
	s_mov_b32 s1, 0
	s_waitcnt lgkmcnt(0)
	s_barrier
; __device__ __forceinline__ void gdn_item(const Params& p, int item, float* sm) {
;     ...
;   for (int ch = 0; ch < NCH; ch++) {
;     const int bi = ch & 1;
;     const int t0 = PADR + ch * TC;
;     if (ch + 1 < NCH) GDN_LOAD(t0 + TC)
;     {
;       const float* bq = sm + bi * BUF;
;       const float* bk = bq + TC * 128;
;       const float* bv = bq + 2 * TC * 128;
;       const float* bg = bv + TC * 16;
;       float* bo = sm + bi * BUF + 2 * TC * 128 + TC * 16 + 2 * TC;
;       float oreg[TC];
; #pragma unroll
;       for (int t = 0; t < TC; t++) {
;         const float4 k0 = *(const float4*)(bk + t * 128 + sub * 4);
;         const float4 k1 = *(const float4*)(bk + t * 128 + 64 + sub * 4);
;         const float4 q0 = *(const float4*)(bq + t * 128 + sub * 4);
;         const float4 q1 = *(const float4*)(bq + t * 128 + 64 + sub * 4);
;         const float v = bv[t * 16 + cw];
;         const float g = bg[t], be = bg[TC + t];
;         const float qk = bo[TC * 16 + t];
;         float pa = k0.x * S[0] + k0.y * S[1];
;         float pb2 = k0.z * S[2] + k0.w * S[3];
;         float qa = q0.x * S[0] + q0.y * S[1];
;         float qb2 = q0.z * S[2] + q0.w * S[3];
;         pa += k1.x * S[4] + k1.y * S[5];
;         pb2 += k1.z * S[6] + k1.w * S[7];
;         qa += q1.x * S[4] + q1.y * S[5];
;         qb2 += q1.z * S[6] + q1.w * S[7];
;         const float ks = dpp_sum16(pa + pb2);
;         const float qs = dpp_sum16(qa + qb2);
;         const float coef = be * (v - g * ks);
;         const float oo = g * qs + coef * qk;
;         S[0] = g * S[0] + coef * k0.x; S[1] = g * S[1] + coef * k0.y; S[2] = g * S[2] + coef * k0.z; S[3] = g * S[3] + coef * k0.w;
;         S[4] = g * S[4] + coef * k1.x; S[5] = g * S[5] + coef * k1.y; S[6] = g * S[6] + coef * k1.z; S[7] = g * S[7] + coef * k1.w;
;         oreg[t] = oo * 0.08838834764831845f;
.Lgd_chunk:
	v_add_u32_e32 v141, s1, v151
	v_add_u32_e32 v142, s1, v152
	v_add_u32_e32 v143, s1, v153
	v_add_u32_e32 v144, s1, v154
	v_mov_b32_e32 v145, s1
	s_xor_b32 s2, s1, 0x4500
	s_and_b32 s12, s0, 1
	s_mul_i32 s12, s12, 0x3000
	v_add_u32_e32 v146, s12, v155
	v_add_u32_e32 v147, s12, v156
	s_xor_b32 s101, s12, 0x3000
	v_add_u32_e32 v178, s101, v184
	ds_read_b128 v[20:23], v141 offset:8192
	ds_read_b128 v[28:31], v141 offset:0
	ds_read_b128 v[24:27], v141 offset:8256
	ds_read_b128 v[32:35], v141 offset:64
	v_add_u32_e32 v148, s2, v157
	v_add_u32_e32 v149, s2, v158
	v_add_u32_e32 v150, s2, v159
	s_waitcnt lgkmcnt(0)
	v_mfma_f32_16x16x4_f32 v[60:63], v20, v12, 0
	ds_read_b32 v36, v142 offset:8192
	v_mfma_f32_16x16x4_f32 v[64:67], v28, v12, 0
	ds_read_b32 v37, v142 offset:8704
	v_mfma_f32_16x16x4_f32 v[60:63], v21, v13, v[60:63]
	ds_read_b32 v38, v142 offset:9216
	v_mfma_f32_16x16x4_f32 v[64:67], v29, v13, v[64:67]
	ds_read_b32 v39, v142 offset:9728
	s_waitcnt vmcnt(0)
	v_lshlrev_b32_e32 v120, 16, v108
	v_and_b32_e32 v121, 0xffff0000, v108
	v_lshlrev_b32_e32 v122, 16, v109
	v_mfma_f32_16x16x4_f32 v[60:63], v22, v14, v[60:63]
	ds_read_b32 v40, v142 offset:8256
	v_and_b32_e32 v123, 0xffff0000, v109
	v_lshlrev_b32_e32 v124, 16, v110
	v_and_b32_e32 v125, 0xffff0000, v110
	v_mfma_f32_16x16x4_f32 v[64:67], v30, v14, v[64:67]
	ds_read_b32 v41, v142 offset:8768
	v_lshlrev_b32_e32 v126, 16, v111
	v_and_b32_e32 v127, 0xffff0000, v111
	v_lshlrev_b32_e32 v128, 16, v112
	v_and_b32_e32 v129, 0xffff0000, v112
	v_mfma_f32_16x16x4_f32 v[60:63], v23, v15, v[60:63]
	ds_read_b32 v42, v142 offset:9280
	v_lshlrev_b32_e32 v130, 16, v113
	v_and_b32_e32 v131, 0xffff0000, v113
	v_lshlrev_b32_e32 v132, 16, v114
	v_mfma_f32_16x16x4_f32 v[64:67], v31, v15, v[64:67]
	ds_read_b32 v43, v142 offset:9792
	v_and_b32_e32 v133, 0xffff0000, v114
	v_lshlrev_b32_e32 v134, 16, v115
	v_and_b32_e32 v135, 0xffff0000, v115
	v_mov_b32_e32 v136, v117
	v_mfma_f32_16x16x4_f32 v[60:63], v24, v16, v[60:63]
	ds_read_b128 v[44:47], v143 offset:16384
	v_lshlrev_b32_e32 v137, 16, v116
	s_nop 0
	v_add_f32_dpp v136, v136, v136 row_shr:1 row_mask:0xf bank_mask:0xf bound_ctrl:1
	v_mfma_f32_16x16x4_f32 v[64:67], v32, v16, v[64:67]
	ds_read_b128 v[48:51], v144 offset:17408
	s_nop 1
	v_add_f32_dpp v136, v136, v136 row_shr:2 row_mask:0xf bank_mask:0xf bound_ctrl:1
	s_nop 1
	v_add_f32_dpp v136, v136, v136 row_shr:4 row_mask:0xf bank_mask:0xf bound_ctrl:1
	v_mfma_f32_16x16x4_f32 v[60:63], v25, v17, v[60:63]
	ds_read_b128 v[52:55], v144 offset:17472
	s_nop 1
	v_add_f32_dpp v136, v136, v136 row_shr:8 row_mask:0xf bank_mask:0xf bound_ctrl:1
	s_nop 0
	v_mfma_f32_16x16x4_f32 v[64:67], v33, v17, v[64:67]
	ds_read_b32 v56, v145 offset:17596
	v_max_f32_e32 v136, 0xc2a00000, v136
	v_mul_f32_e32 v136, 0x3fb8aa3b, v136
	v_exp_f32_e32 v138, v136
	v_exp_f32_e64 v139, -v136
	v_mfma_f32_16x16x4_f32 v[60:63], v26, v18, v[60:63]
	s_nop 0
	v_mul_f32_e32 v136, 0x3db504f3, v138
	ds_write_b128 v148, v[120:123]
	v_mfma_f32_16x16x4_f32 v[64:67], v34, v18, v[64:67]
	ds_write_b128 v148, v[124:127] offset:16
	ds_write_b128 v148, v[128:131] offset:8192
	ds_write_b128 v148, v[132:135] offset:8208
	ds_write_b32 v149, v137
	v_mfma_f32_16x16x4_f32 v[60:63], v27, v19, v[60:63]
	ds_write_b32 v150, v139 offset:17408
	ds_write_b32 v150, v138 offset:17536
	ds_write_b32 v150, v136 offset:17472
	v_mfma_f32_16x16x4_f32 v[64:67], v35, v19, v[64:67]
	global_load_dwordx4 v[108:111], v118, s[4:5]
	global_load_dwordx4 v[112:115], v118, s[4:5] offset:1024
	global_load_ushort v116, v119, s[4:5]
	global_load_dword v117, v140, s[6:7]
	s_cmp_lt_u32 s0, 0x1fe
	s_cselect_b32 s12, 0xc000, 0
	s_cselect_b32 s101, 0x200, 0
	s_add_u32 s4, s4, s12
	s_addc_u32 s5, s5, 0
	s_add_u32 s6, s6, s101
	s_addc_u32 s7, s7, 0
	s_nop 3
	ds_write_b128 v146, v[60:63]
	s_waitcnt lgkmcnt(0)
	s_barrier
; __device__ __forceinline__ void gdn_item(const Params& p, int item, float* sm) {
;     ...
;         const float ks = dpp_sum16(pa + pb2);
;         const float qs = dpp_sum16(qa + qb2);
;         const float coef = be * (v - g * ks);
;         const float oo = g * qs + coef * qk;
;         S[0] = g * S[0] + coef * k0.x; S[1] = g * S[1] + coef * k0.y; S[2] = g * S[2] + coef * k0.z; S[3] = g * S[3] + coef * k0.w;
;         S[4] = g * S[4] + coef * k1.x; S[5] = g * S[5] + coef * k1.y; S[6] = g * S[6] + coef * k1.z; S[7] = g * S[7] + coef * k1.w;
;         oreg[t] = oo * 0.08838834764831845f;
;       }
;       if (sub == 0) {
; #pragma unroll
;         for (int t = 0; t < TC; t++) bo[t * 16 + cw] = oreg[t];
;       }
;     }
;     if (ch + 1 < NCH) GDN_STORE(bi ^ 1)
;     __syncthreads();
;     {
;       const float ov = sm[bi * BUF + 2 * TC * 128 + TC * 16 + 2 * TC + ltt * 16 + lseg];
;       O[(rowb + t0 + ltt) * D + 512 + h * 128 + c0 + lseg] = f2bf(ov);
;     }
;   }
;     ...
;   __syncthreads();
	ds_read_b128 v[72:75], v147 offset:0
	ds_read_b128 v[76:79], v147 offset:3072
	ds_read_b128 v[80:83], v147 offset:6144
	ds_read_b128 v[84:87], v147 offset:9216
	ds_read_b32 v180, v178 offset:0
	ds_read_b32 v181, v178 offset:3072
	ds_read_b32 v182, v178 offset:6144
	ds_read_b32 v183, v178 offset:9216
	s_waitcnt lgkmcnt(4)
	v_add_f32_e32 v72, v72, v76
	v_add_f32_e32 v80, v80, v84
	v_add_f32_e32 v73, v73, v77
	v_add_f32_e32 v81, v81, v85
	v_add_f32_e32 v74, v74, v78
	v_add_f32_e32 v82, v82, v86
	v_add_f32_e32 v75, v75, v79
	v_add_f32_e32 v83, v83, v87
	v_add_f32_e32 v72, v72, v80
	v_add_f32_e32 v73, v73, v81
	v_add_f32_e32 v74, v74, v82
	v_add_f32_e32 v75, v75, v83
	v_fma_f32 v96, v44, v48, -v72
	v_fma_f32 v97, v45, v49, -v73
	v_fma_f32 v98, v46, v50, -v74
	v_fma_f32 v99, v47, v51, -v75
	s_nop 1
	v_mfma_f32_16x16x4_f32 v[100:103], v88, v96, 0
	v_mfma_f32_16x16x4_f32 v[100:103], v89, v97, v[100:103]
	v_mfma_f32_16x16x4_f32 v[100:103], v90, v98, v[100:103]
	v_mfma_f32_16x16x4_f32 v[100:103], v91, v99, v[100:103]
	global_load_dwordx4 v[88:91], v59, s[10:11]
	s_cmp_lt_u32 s0, 0x1ff
	s_cselect_b32 s12, 0x400, 0
	s_add_u32 s10, s10, s12
	s_addc_u32 s11, s11, 0
	v_mul_f32_e32 v186, v174, v170
	v_fmac_f32_e32 v186, v175, v171
	v_fmac_f32_e32 v186, v176, v172
	v_fmac_f32_e32 v186, v177, v173
	s_waitcnt lgkmcnt(0)
	v_add_f32_e32 v180, v180, v181
	v_add_f32_e32 v182, v182, v183
	v_add_f32_e32 v180, v180, v182
	v_mul_f32_e32 v180, v180, v186
	v_cvt_pk_bf16_f32 v180, v180, v180
	s_cmp_lg_u32 s0, 0
	s_cselect_b64 exec, -1, 0
	global_store_short v185, v180, s[8:9]
	s_mov_b64 exec, -1
	s_add_u32 s8, s8, 0x8000
	s_addc_u32 s9, s9, 0
	v_mfma_f32_16x16x4_f32 v[12:15], v36, v100, v[12:15]
	v_mfma_f32_16x16x4_f32 v[16:19], v40, v100, v[16:19]
	v_mfma_f32_16x16x4_f32 v[12:15], v37, v101, v[12:15]
	v_mfma_f32_16x16x4_f32 v[16:19], v41, v101, v[16:19]
	v_mfma_f32_16x16x4_f32 v[12:15], v38, v102, v[12:15]
	v_mfma_f32_16x16x4_f32 v[16:19], v42, v102, v[16:19]
	v_mfma_f32_16x16x4_f32 v[12:15], v39, v103, v[12:15]
	v_mfma_f32_16x16x4_f32 v[16:19], v43, v103, v[16:19]
	v_mul_f32_e32 v93, v100, v170
	v_fmac_f32_e32 v93, v101, v171
	v_fmac_f32_e32 v93, v102, v172
	v_fmac_f32_e32 v93, v103, v173
	v_mov_b32_e32 v174, v52
	v_mov_b32_e32 v175, v53
	v_mov_b32_e32 v176, v54
	v_mov_b32_e32 v177, v55
	v_mfma_f32_16x16x4_f32 v[64:67], v92, v93, v[64:67]
	global_load_dword v92, v179, s[14:15]
	s_cmp_lt_u32 s0, 0x1ff
	s_cselect_b32 s101, 0x400, 0
	s_add_u32 s14, s14, s101
	s_addc_u32 s15, s15, 0
	s_nop 1
	v_mul_f32_e32 v12, v12, v56
	v_mul_f32_e32 v13, v13, v56
	v_mul_f32_e32 v14, v14, v56
	v_mul_f32_e32 v15, v15, v56
	v_mul_f32_e32 v16, v16, v56
	v_mul_f32_e32 v17, v17, v56
	v_mul_f32_e32 v18, v18, v56
	v_mul_f32_e32 v19, v19, v56
	s_nop 1
	ds_write_b128 v146, v[64:67] offset:1024
	s_mov_b32 s1, s2
	s_add_i32 s0, s0, 1
	s_cmp_lg_u32 s0, 513
	s_cbranch_scc1 .Lgd_chunk
	s_waitcnt vmcnt(0) lgkmcnt(0)
	s_barrier
	ds_read_b32 v180, v184 offset:0
	ds_read_b32 v181, v184 offset:3072
	ds_read_b32 v182, v184 offset:6144
	ds_read_b32 v183, v184 offset:9216
	v_mul_f32_e32 v186, v174, v170
	v_fmac_f32_e32 v186, v175, v171
	v_fmac_f32_e32 v186, v176, v172
	v_fmac_f32_e32 v186, v177, v173
	s_waitcnt lgkmcnt(0)
	v_add_f32_e32 v180, v180, v181
	v_add_f32_e32 v182, v182, v183
	v_add_f32_e32 v180, v180, v182
	v_mul_f32_e32 v180, v180, v186
	v_cvt_pk_bf16_f32 v180, v180, v180
	global_store_short v185, v180, s[8:9]
	s_waitcnt vmcnt(0) lgkmcnt(0)
	s_setprio 0
